# grid barrier: non-leader workgroups poll the cross-XCD release word (TOPGEN) directly instead of their XCD's generation word (one dependent round trip less per seam, 9 seams); on top of all23
# speedup vs baseline: 1.0096x; 1.0042x over previous
; __device__ __forceinline__ int lane_id_asm() { int l; asm volatile("v_mbcnt_lo_u32_b32 %0, -1, 0\n\tv_mbcnt_hi_u32_b32 %0, -1, %0" : "=v"(l)); return l; }
; __device__ __forceinline__ unsigned xb_ld(unsigned* p)              { return __hip_atomic_load(p, __ATOMIC_RELAXED, __HIP_MEMORY_SCOPE_AGENT); }
; __device__ __forceinline__ unsigned xb_add(unsigned* p, unsigned v) { return __hip_atomic_fetch_add(p, v, __ATOMIC_RELAXED, __HIP_MEMORY_SCOPE_AGENT); }
; #define XB_SPIN(cond, bar) do { unsigned _sp = 0; while (cond) { __builtin_amdgcn_s_sleep(1); \
;     if ((++_sp & 255u) == 0u) { if (xb_ld(&(bar)[XB_TMO])) break; if (_sp > XB_SPIN_CAP) { atomicAdd(&(bar)[XB_TMO], 1u); break; } } } } while (0)
; __device__ __forceinline__ void xcd_barrier(const XcdBarrier& b, const int wid) {
;     ...
;     if (wid == 0 && lane_id_asm() == 0) {
;         unsigned* bar = b.bar;
;         __builtin_amdgcn_s_waitcnt(0);
;         unsigned nloc = b.st[0], nx = b.st[1];
;         if (nloc == 0u) { xcd_barrier_complete(bar, b.x, nloc, nx); b.st[0] = nloc; b.st[1] = nx; }
;         const unsigned old = xb_add(&bar[XB_XSUB(b.x)], 1u);
;         const unsigned gen = old / nloc;
;         if (old + 1u == (gen + 1u) * nloc) {
;             __builtin_amdgcn_fence(__ATOMIC_RELEASE, "agent");
;             asm volatile("s_waitcnt vmcnt(0)" ::: "memory");
;             const unsigned og = xb_add(&bar[XB_TOP], 1u);
;             const unsigned tg = og / nx;
;             if (og + 1u == (tg + 1u) * nx) xb_add(&bar[XB_TOPGEN], 1u);
;             else XB_SPIN(xb_ld(&bar[XB_TOPGEN]) == tg, bar);
;             __builtin_amdgcn_fence(__ATOMIC_ACQUIRE, "agent");
;             xb_add(&bar[XB_XGEN(b.x)], 1u);
;             asm volatile("s_waitcnt vmcnt(0)" ::: "memory");
;         } else {
;             XB_SPIN(xb_ld(&bar[XB_XGEN(b.x)]) == gen, bar);
;             __builtin_amdgcn_fence(__ATOMIC_ACQUIRE, "agent");
;             asm volatile("s_waitcnt vmcnt(0)" ::: "memory");
;         }
.LBB0_225:
	v_readlane_b32 s2, v254, 8
	s_lshl_b32 s2, s2, 8
	v_readlane_b32 s4, v254, 6
	v_readlane_b32 s5, v254, 7
	s_add_u32 s2, s4, s2
	s_addc_u32 s3, s5, 0
	v_mov_b32_e32 v1, 0x1000
	v_mov_b32_e32 v3, 1
	global_atomic_add v3, v1, v3, s[2:3] offset:1024 sc0
	v_cvt_f32_u32_e32 v1, v2
	v_sub_u32_e32 v4, 0, v2
	v_rcp_iflag_f32_e32 v1, v1
	s_nop 0
	v_mul_f32_e32 v1, 0x4f7ffffe, v1
	v_cvt_u32_f32_e32 v1, v1
	v_mul_lo_u32 v4, v4, v1
	v_mul_hi_u32 v4, v1, v4
	v_add_u32_e32 v1, v1, v4
	s_waitcnt vmcnt(0)
	v_mul_hi_u32 v1, v3, v1
	v_mul_lo_u32 v4, v1, v2
	v_sub_u32_e32 v4, v3, v4
	v_add_u32_e32 v5, 1, v1
	v_cmp_ge_u32_e32 vcc, v4, v2
	v_add_u32_e32 v3, 1, v3
	s_nop 0
	v_cndmask_b32_e32 v1, v1, v5, vcc
	v_sub_u32_e32 v5, v4, v2
	v_cndmask_b32_e32 v4, v4, v5, vcc
	v_add_u32_e32 v5, 1, v1
	v_cmp_ge_u32_e32 vcc, v4, v2
	s_nop 1
	v_cndmask_b32_e32 v1, v1, v5, vcc
	v_mul_lo_u32 v4, v2, v1
	v_add_u32_e32 v2, v4, v2
	v_cmp_ne_u32_e32 vcc, v3, v2
	s_and_saveexec_b64 s[4:5], vcc
	s_xor_b64 s[4:5], exec, s[4:5]
	s_cbranch_execz .LBB0_239
	s_waitcnt lgkmcnt(0)
	v_mov_b32_e32 v0, 0
	s_add_u32 s10, s86, 0x7500
	s_addc_u32 s11, s87, 0
	global_load_dword v0, v0, s[10:11] sc1
	s_waitcnt vmcnt(0)
	v_cmp_eq_u32_e32 vcc, v0, v1
	s_and_saveexec_b64 s[6:7], vcc
	s_cbranch_execz .LBB0_238
	s_add_u32 s8, s86, 0x4200
	s_addc_u32 s9, s87, 0
	s_mov_b32 s22, 1
	s_mov_b64 s[12:13], 0
	v_mov_b32_e32 v0, 0
	s_branch .LBB0_229
